# attention loops: cross-half row max via v_permlane32_swap instead of LDS bpermute
# baseline (speedup 1.0000x reference)
; DI float ex2(float x) { return __builtin_amdgcn_exp2f(x); }
; DI int crow(int reg, int h) { return (reg & 3) + 8 * (reg >> 2) + 4 * h; }
; template <int DQK, bool NA>
; DI void attn_unit(const bf16_t* __restrict__ Qb, int ldq, const bf16_t* __restrict__ Kb, int ldk, const bf16_t* __restrict__ Vt,
;                   bf16_t* __restrict__ Ob, int ldo, int u, float sc, const float* __restrict__ rpb_h, char* smem) {
;     ...
;       if (NA) {
;         const int brow = (kt - rq + 7) * 31;
; #pragma unroll
;         for (int q = 0; q < 16; ++q) {
;           int kc0 = crow(q, h), kc1 = 32 + kc0;
;           bool v0 = (kc0 >= cs) && (kc0 < cs + 16), v1 = (kc1 >= cs) && (kc1 < cs + 16);
;           float b0 = v0 ? sBias[brow + kc0 - cq + 15] : 0.f;
;           float b1 = v1 ? sBias[brow + kc1 - cq + 15] : 0.f;
;           s0[q] = v0 ? (s0[q] * sc + b0) : -INFINITY;
;           s1[q] = v1 ? (s1[q] * sc + b1) : -INFINITY;
;         }
;       }
;       float mx = s0[0];
; #pragma unroll
;       for (int q = 1; q < 16; ++q) mx = fmaxf(mx, s0[q]);
; #pragma unroll
;       for (int q = 0; q < 16; ++q) mx = fmaxf(mx, s1[q]);
;       mx = fmaxf(mx, __shfl_xor(mx, 32));
;       if (__builtin_amdgcn_ballot_w64((mx - m_run) > 8.f) != 0ull) {
;         const float m_new = fmaxf(m_run, mx);
;         const float alpha = ex2(m_run - m_new);
;         m_run = m_new;
;         l_run *= alpha;
; #pragma unroll
;         for (int q = 0; q < 16; ++q) { o0[q] *= alpha; o1[q] *= alpha; }
;       }
.LBB0_357:
	s_or_b64 exec, exec, vcc
	s_waitcnt lgkmcnt(0)
	v_fmac_f32_e32 v5, 0x3e38aa3b, v65
	v_fmac_f32_e32 v3, 0x3e38aa3b, v64
	v_fmac_f32_e32 v145, 0x3e38aa3b, v67
	v_fmac_f32_e32 v143, 0x3e38aa3b, v66
	v_cndmask_b32_e64 v65, v5, v129, s[10:11]
	v_cndmask_b32_e64 v64, v3, v129, s[6:7]
	v_fmac_f32_e32 v4, 0x3e38aa3b, v62
	v_fmac_f32_e32 v149, 0x3e38aa3b, v69
	v_fmac_f32_e32 v147, 0x3e38aa3b, v68
	v_cndmask_b32_e64 v67, v145, v129, s[22:23]
	v_cndmask_b32_e64 v66, v143, v129, s[16:17]
	v_max_f32_e32 v62, v64, v65
	v_fmac_f32_e32 v9, 0x3e38aa3b, v61
	v_fmac_f32_e32 v8, 0x3e38aa3b, v60
	v_fmac_f32_e32 v153, 0x3e38aa3b, v71
	v_fmac_f32_e32 v151, 0x3e38aa3b, v70
	v_cndmask_b32_e64 v61, v149, v129, s[36:37]
	v_cndmask_b32_e64 v60, v147, v129, s[28:29]
	v_max3_f32 v62, v62, v66, v67
	v_fmac_f32_e32 v13, 0x3e38aa3b, v59
	v_fmac_f32_e32 v12, 0x3e38aa3b, v58
	v_fmac_f32_e32 v15, 0x3e38aa3b, v73
	v_fmac_f32_e32 v14, 0x3e38aa3b, v72
	v_cndmask_b32_e64 v59, v153, v129, s[48:49]
	v_cndmask_b32_e64 v58, v151, v129, s[42:43]
	v_max3_f32 v62, v62, v60, v61
	v_fmac_f32_e32 v11, 0x3e38aa3b, v75
	v_fmac_f32_e32 v10, 0x3e38aa3b, v74
	v_cndmask_b32_e64 v15, v129, v15, s[58:59]
	v_cndmask_b32_e64 v14, v129, v14, s[54:55]
	v_max3_f32 v62, v62, v58, v59
	v_fmac_f32_e32 v7, 0x3e38aa3b, v77
	v_fmac_f32_e32 v6, 0x3e38aa3b, v76
	v_cndmask_b32_e64 v11, v129, v11, s[66:67]
	v_cndmask_b32_e64 v10, v129, v10, s[62:63]
	v_max3_f32 v62, v62, v14, v15
	v_fmac_f32_e32 v2, 0x3e38aa3b, v78
	v_cndmask_b32_e64 v7, v129, v7, s[74:75]
	v_cndmask_b32_e64 v6, v129, v6, s[70:71]
	v_fmac_f32_e32 v157, 0x3e38aa3b, v79
	v_max3_f32 v62, v62, v10, v11
	v_cndmask_b32_e64 v2, v129, v2, s[78:79]
	v_fmac_f32_e32 v142, 0x3e38aa3b, v49
	v_fmac_f32_e32 v117, 0x3e38aa3b, v48
	v_cndmask_b32_e64 v3, v129, v157, s[80:81]
	v_max3_f32 v62, v62, v6, v7
	v_fmac_f32_e32 v146, 0x3e38aa3b, v51
	v_fmac_f32_e32 v144, 0x3e38aa3b, v50
	v_cndmask_b32_e64 v49, v129, v142, s[14:15]
	v_cndmask_b32_e64 v48, v129, v117, s[8:9]
	v_max3_f32 v62, v62, v2, v3
	v_fmac_f32_e32 v150, 0x3e38aa3b, v53
	v_fmac_f32_e32 v148, 0x3e38aa3b, v52
	v_cndmask_b32_e64 v51, v129, v146, s[26:27]
	v_cndmask_b32_e64 v50, v129, v144, s[20:21]
	v_max3_f32 v62, v62, v48, v49
	v_fmac_f32_e32 v154, 0x3e38aa3b, v55
	v_fmac_f32_e32 v152, 0x3e38aa3b, v54
	v_cndmask_b32_e64 v53, v129, v150, s[40:41]
	v_cndmask_b32_e64 v52, v129, v148, s[34:35]
	v_max3_f32 v62, v62, v50, v51
	v_fmac_f32_e32 v156, 0x3e38aa3b, v57
	v_fmac_f32_e32 v155, 0x3e38aa3b, v56
	v_cndmask_b32_e64 v55, v129, v154, s[52:53]
	v_cndmask_b32_e64 v54, v129, v152, s[46:47]
	v_max3_f32 v62, v62, v52, v53
	v_cndmask_b32_e64 v57, v129, v156, s[60:61]
	v_cndmask_b32_e64 v56, v129, v155, s[56:57]
	v_max3_f32 v62, v62, v54, v55
	v_and_b32_e32 v68, 64, v197
	v_cndmask_b32_e64 v13, v129, v13, s[68:69]
	v_cndmask_b32_e64 v12, v129, v12, s[64:65]
	v_fmac_f32_e32 v158, 0x3e38aa3b, v63
	v_max3_f32 v62, v62, v56, v57
	v_xor_b32_e32 v63, 32, v197
	v_add_u32_e32 v68, 64, v68
	v_cndmask_b32_e64 v9, v129, v9, s[76:77]
	v_cndmask_b32_e64 v8, v129, v8, s[72:73]
	v_max3_f32 v62, v62, v12, v13
	v_cmp_lt_i32_e32 vcc, v63, v68
	v_cndmask_b32_e64 v4, v129, v4, s[82:83]
	v_cndmask_b32_e64 v5, v129, v158, s[84:85]
	v_max3_f32 v62, v62, v8, v9
	v_cndmask_b32_e32 v63, v197, v63, vcc
	v_max3_f32 v62, v62, v4, v5
	v_lshlrev_b32_e32 v63, 2, v63
	v_mov_b32_e32 v63, v62
	s_nop 1
	v_permlane32_swap_b32_e32 v63, v62
	v_max_f32_e32 v62, v62, v63
	v_sub_f32_e32 v63, v62, v124
	v_cmp_lt_f32_e32 vcc, s0, v63
	s_cbranch_vccz .LBB0_359
	v_max_f32_e32 v62, v62, v62
	v_max_f32_e32 v63, v124, v124
	v_max_f32_e32 v63, v63, v62
	v_sub_f32_e32 v62, v124, v63
	v_exp_f32_e32 v62, v62
	v_mov_b32_e32 v124, v63
	v_pk_mul_f32 v[46:47], v[46:47], v[62:63] op_sel_hi:[1,0]
	v_pk_mul_f32 v[44:45], v[44:45], v[62:63] op_sel_hi:[1,0]
	v_pk_mul_f32 v[42:43], v[42:43], v[62:63] op_sel_hi:[1,0]
	v_pk_mul_f32 v[40:41], v[40:41], v[62:63] op_sel_hi:[1,0]
	v_pk_mul_f32 v[38:39], v[38:39], v[62:63] op_sel_hi:[1,0]
	v_pk_mul_f32 v[36:37], v[36:37], v[62:63] op_sel_hi:[1,0]
	v_pk_mul_f32 v[34:35], v[34:35], v[62:63] op_sel_hi:[1,0]
	v_pk_mul_f32 v[32:33], v[32:33], v[62:63] op_sel_hi:[1,0]
	v_pk_mul_f32 v[30:31], v[30:31], v[62:63] op_sel_hi:[1,0]
	v_pk_mul_f32 v[28:29], v[28:29], v[62:63] op_sel_hi:[1,0]
	v_pk_mul_f32 v[26:27], v[26:27], v[62:63] op_sel_hi:[1,0]
	v_pk_mul_f32 v[24:25], v[24:25], v[62:63] op_sel_hi:[1,0]
	v_pk_mul_f32 v[22:23], v[22:23], v[62:63] op_sel_hi:[1,0]
	v_pk_mul_f32 v[20:21], v[20:21], v[62:63] op_sel_hi:[1,0]
	v_pk_mul_f32 v[18:19], v[18:19], v[62:63] op_sel_hi:[1,0]
	v_pk_mul_f32 v[16:17], v[16:17], v[62:63] op_sel_hi:[1,0]
	v_mul_f32_e32 v140, v140, v62

; #define MFMA32(a, b, c) __builtin_amdgcn_mfma_f32_32x32x16_bf16(__builtin_bit_cast(bf16x8, (a)), __builtin_bit_cast(bf16x8, (b)), (c), 0, 0, 0)
; DI float ex2(float x) { return __builtin_amdgcn_exp2f(x); }
; DI int crow(int reg, int h) { return (reg & 3) + 8 * (reg >> 2) + 4 * h; }
; template <int DQK, bool NA>
; DI void attn_unit(const bf16_t* __restrict__ Qb, int ldq, const bf16_t* __restrict__ Kb, int ldk, const bf16_t* __restrict__ Vt,
;                   bf16_t* __restrict__ Ob, int ldo, int u, float sc, const float* __restrict__ rpb_h, char* smem) {
;     ...
;       {
;         const f32x16 zero16 = {0.f, 0.f, 0.f, 0.f, 0.f, 0.f, 0.f, 0.f, 0.f, 0.f, 0.f, 0.f, 0.f, 0.f, 0.f, 0.f};
;         u32x4 k0 = *(const u32x4*)(cK);
;         u32x4 k1 = *(const u32x4*)(cK + 32 * KS);
;         s0 = MFMA32(k0, qf[0], zero16);
;         s1 = MFMA32(k1, qf[0], zero16);
;       }
; #pragma unroll
;       for (int ds = 1; ds < NDS; ++ds) {
;         u32x4 k0 = *(const u32x4*)(cK + ds * 16);
;         u32x4 k1 = *(const u32x4*)(cK + 32 * KS + ds * 16);
;         s0 = MFMA32(k0, qf[ds], s0);
;         s1 = MFMA32(k1, qf[ds], s1);
;       }
;       if (NA) {
;         const int brow = (kt - rq + 7) * 31;
; #pragma unroll
;         for (int q = 0; q < 16; ++q) {
;           int kc0 = crow(q, h), kc1 = 32 + kc0;
;           bool v0 = (kc0 >= cs) && (kc0 < cs + 16), v1 = (kc1 >= cs) && (kc1 < cs + 16);
;           float b0 = v0 ? sBias[brow + kc0 - cq + 15] : 0.f;
;           float b1 = v1 ? sBias[brow + kc1 - cq + 15] : 0.f;
;           s0[q] = v0 ? (s0[q] * sc + b0) : -INFINITY;
;           s1[q] = v1 ? (s1[q] * sc + b1) : -INFINITY;
;         }
;       }
;       float mx = s0[0];
; #pragma unroll
;       for (int q = 1; q < 16; ++q) mx = fmaxf(mx, s0[q]);
; #pragma unroll
;       for (int q = 0; q < 16; ++q) mx = fmaxf(mx, s1[q]);
;       mx = fmaxf(mx, __shfl_xor(mx, 32));
;       if (__builtin_amdgcn_ballot_w64((mx - m_run) > 8.f) != 0ull) {
;         const float m_new = fmaxf(m_run, mx);
;         const float alpha = ex2(m_run - m_new);
;         m_run = m_new;
;         l_run *= alpha;
; #pragma unroll
;         for (int q = 0; q < 16; ++q) { o0[q] *= alpha; o1[q] *= alpha; }
;       }
.LBB0_382:
	s_or_b64 exec, exec, s[2:3]
	s_and_b32 s2, s1, 1
	s_mul_i32 s3, s2, 0x3400
	v_add_u32_e32 v0, s3, v135
	ds_read_b128 v[6:9], v0
	ds_read_b128 v[10:13], v0 offset:32
	s_waitcnt lgkmcnt(1)
	v_mfma_f32_32x32x16_bf16 v[64:79], v[6:9], v[100:103], 0
	ds_read_b128 v[6:9], v0 offset:6656
	ds_read_b128 v[140:143], v0 offset:6688
	s_waitcnt lgkmcnt(2)
	v_mfma_f32_32x32x16_bf16 v[64:79], v[10:13], v[96:99], v[64:79]
	s_waitcnt lgkmcnt(1)
	v_mfma_f32_32x32x16_bf16 v[48:63], v[6:9], v[100:103], 0
	ds_read_b128 v[6:9], v0 offset:64
	ds_read_b128 v[10:13], v0 offset:96
	s_waitcnt lgkmcnt(1)
	v_mfma_f32_32x32x16_bf16 v[64:79], v[6:9], v[92:95], v[64:79]
	s_waitcnt lgkmcnt(0)
	v_mfma_f32_32x32x16_bf16 v[64:79], v[10:13], v[88:91], v[64:79]
	ds_read_b128 v[6:9], v0 offset:128
	ds_read_b128 v[10:13], v0 offset:160
	s_waitcnt lgkmcnt(1)
	v_mfma_f32_32x32x16_bf16 v[64:79], v[6:9], v[84:87], v[64:79]
	v_mfma_f32_32x32x16_bf16 v[48:63], v[140:143], v[96:99], v[48:63]
	s_waitcnt lgkmcnt(0)
	v_mfma_f32_32x32x16_bf16 v[64:79], v[10:13], v[80:83], v[64:79]
	ds_read_b128 v[6:9], v0 offset:6720
	ds_read_b128 v[10:13], v0 offset:6752
	s_waitcnt lgkmcnt(1)
	v_mfma_f32_32x32x16_bf16 v[48:63], v[6:9], v[92:95], v[48:63]
	global_load_dwordx4 v[6:9], v[116:117], off
	s_nop 6
	v_max_f32_e32 v14, v64, v64
	s_waitcnt lgkmcnt(0)
	v_mfma_f32_32x32x16_bf16 v[48:63], v[10:13], v[88:91], v[48:63]
	ds_read_b128 v[10:13], v0 offset:6784
	ds_read_b128 v[140:143], v0 offset:6816
	v_max_f32_e32 v0, v65, v65
	v_max_f32_e32 v0, v14, v0
	v_max3_f32 v0, v0, v66, v67
	v_max3_f32 v0, v0, v68, v69
	v_max3_f32 v0, v0, v70, v71
	v_max3_f32 v0, v0, v72, v73
	s_waitcnt lgkmcnt(1)
	v_mfma_f32_32x32x16_bf16 v[48:63], v[10:13], v[84:87], v[48:63]
	v_max3_f32 v0, v0, v74, v75
	v_max3_f32 v0, v0, v76, v77
	v_max3_f32 v0, v0, v78, v79
	s_waitcnt lgkmcnt(0)
	v_mfma_f32_32x32x16_bf16 v[48:63], v[140:143], v[80:83], v[48:63]
	s_nop 11
	v_max3_f32 v0, v0, v48, v49
	v_max3_f32 v0, v0, v50, v51
	v_max3_f32 v0, v0, v52, v53
	v_max3_f32 v0, v0, v54, v55
	v_max3_f32 v0, v0, v56, v57
	v_max3_f32 v0, v0, v58, v59
	v_max3_f32 v0, v0, v60, v61
	v_max3_f32 v0, v0, v62, v63
	v_mov_b32_e32 v10, v0
	s_nop 1
	v_permlane32_swap_b32_e32 v10, v0
	v_max_f32_e32 v0, v0, v10
	v_sub_f32_e32 v10, v0, v120
	v_cmp_lt_f32_e32 vcc, s0, v10
	s_cbranch_vccz .LBB0_384
	v_max_f32_e32 v0, v0, v0
	v_max_f32_e32 v10, v120, v120
	v_max_f32_e32 v10, v10, v0
	v_sub_f32_e32 v0, v120, v10
	v_exp_f32_e32 v0, v0
	v_mov_b32_e32 v120, v10
	v_pk_mul_f32 v[46:47], v[46:47], v[0:1] op_sel_hi:[1,0]
	v_pk_mul_f32 v[44:45], v[44:45], v[0:1] op_sel_hi:[1,0]
	v_pk_mul_f32 v[42:43], v[42:43], v[0:1] op_sel_hi:[1,0]
	v_pk_mul_f32 v[40:41], v[40:41], v[0:1] op_sel_hi:[1,0]
	v_pk_mul_f32 v[38:39], v[38:39], v[0:1] op_sel_hi:[1,0]
	v_pk_mul_f32 v[36:37], v[36:37], v[0:1] op_sel_hi:[1,0]
	v_pk_mul_f32 v[34:35], v[34:35], v[0:1] op_sel_hi:[1,0]
	v_pk_mul_f32 v[32:33], v[32:33], v[0:1] op_sel_hi:[1,0]
	v_pk_mul_f32 v[30:31], v[30:31], v[0:1] op_sel_hi:[1,0]
	v_pk_mul_f32 v[28:29], v[28:29], v[0:1] op_sel_hi:[1,0]
	v_pk_mul_f32 v[26:27], v[26:27], v[0:1] op_sel_hi:[1,0]
	v_pk_mul_f32 v[24:25], v[24:25], v[0:1] op_sel_hi:[1,0]
	v_pk_mul_f32 v[22:23], v[22:23], v[0:1] op_sel_hi:[1,0]
	v_pk_mul_f32 v[20:21], v[20:21], v[0:1] op_sel_hi:[1,0]
	v_pk_mul_f32 v[18:19], v[18:19], v[0:1] op_sel_hi:[1,0]
	v_pk_mul_f32 v[16:17], v[16:17], v[0:1] op_sel_hi:[1,0]
	v_mul_f32_e32 v115, v115, v0
